# prep phase: second row block g-GEMM fragment loads issued together (was serialized load/wait per K-slice)
# speedup vs baseline: 1.0123x; 1.0105x over previous
.LBB0_836:
	s_or_b64 exec, exec, s[2:3]
	global_load_dwordx4 v[0:3], v[58:59], off offset:256
	global_load_dwordx4 v[92:95], v[58:59], off offset:320
	global_load_dwordx4 v[96:99], v[58:59], off offset:384
	global_load_dwordx4 v[100:103], v[58:59], off offset:448
	ds_read_b128 v[4:7], v140 offset:32768
	ds_read_b128 v[8:11], v140 offset:36864
	ds_read_b128 v[12:15], v140 offset:40960
	ds_read_b128 v[16:19], v140 offset:45056
	ds_read_b128 v[104:107], v141 offset:32768
	ds_read_b128 v[108:111], v141 offset:36864
	ds_read_b128 v[112:115], v141 offset:40960
	ds_read_b128 v[116:119], v141 offset:45056
	ds_read_b128 v[156:159], v142 offset:32768
	ds_read_b128 v[160:163], v142 offset:36864
	ds_read_b128 v[164:167], v142 offset:40960
	ds_read_b128 v[168:171], v142 offset:45056
	s_add_i32 s4, s4, s50
	s_add_i32 s5, s5, s6
	s_add_i32 s7, s7, s8
	v_add_u32_e32 v125, s91, v125
	s_cmpk_lt_i32 s4, 0x1e0
	s_waitcnt vmcnt(3) lgkmcnt(8)
	v_mfma_f32_16x16x32_bf16 v[4:7], v[0:3], v[4:7], 0
	v_mfma_f32_16x16x32_bf16 v[8:11], v[0:3], v[8:11], 0
	v_mfma_f32_16x16x32_bf16 v[12:15], v[0:3], v[12:15], 0
	v_mfma_f32_16x16x32_bf16 v[0:3], v[0:3], v[16:19], 0
	ds_read_b128 v[172:175], v143 offset:32768
	ds_read_b128 v[176:179], v143 offset:36864
	ds_read_b128 v[180:183], v143 offset:40960
	ds_read_b128 v[184:187], v143 offset:45056
	s_waitcnt vmcnt(2) lgkmcnt(8)
	v_mfma_f32_16x16x32_bf16 v[4:7], v[92:95], v[104:107], v[4:7]
	v_mfma_f32_16x16x32_bf16 v[8:11], v[92:95], v[108:111], v[8:11]
	v_mfma_f32_16x16x32_bf16 v[12:15], v[92:95], v[112:115], v[12:15]
	v_mfma_f32_16x16x32_bf16 v[0:3], v[92:95], v[116:119], v[0:3]
	s_waitcnt vmcnt(1) lgkmcnt(4)
	v_mfma_f32_16x16x32_bf16 v[4:7], v[96:99], v[156:159], v[4:7]
	v_mfma_f32_16x16x32_bf16 v[8:11], v[96:99], v[160:163], v[8:11]
	v_mfma_f32_16x16x32_bf16 v[12:15], v[96:99], v[164:167], v[12:15]
	v_mfma_f32_16x16x32_bf16 v[0:3], v[96:99], v[168:171], v[0:3]
	s_waitcnt vmcnt(0) lgkmcnt(0)
	v_mfma_f32_16x16x32_bf16 v[4:7], v[100:103], v[172:175], v[4:7]
	v_mfma_f32_16x16x32_bf16 v[8:11], v[100:103], v[176:179], v[8:11]
	v_mfma_f32_16x16x32_bf16 v[12:15], v[100:103], v[180:183], v[12:15]
	v_mfma_f32_16x16x32_bf16 v[0:3], v[100:103], v[184:187], v[0:3]
	s_nop 7
	s_nop 1
	v_cvt_pk_bf16_f32 v4, v4, s0
	v_cvt_pk_bf16_f32 v6, v6, s0
	v_lshl_add_u64 v[16:17], v[62:63], 1, s[56:57]
	global_store_short v[16:17], v4, off
	v_cvt_pk_bf16_f32 v16, v5, s0
	v_lshl_add_u64 v[4:5], v[66:67], 1, s[56:57]
	global_store_short v[4:5], v16, off
	v_lshl_add_u64 v[4:5], v[72:73], 1, s[56:57]
	global_store_short v[4:5], v6, off
	v_cvt_pk_bf16_f32 v6, v7, s0
	v_lshl_add_u64 v[4:5], v[52:53], 1, s[56:57]
	global_store_short v[4:5], v6, off
	v_cvt_pk_bf16_f32 v6, v8, s0
	v_lshl_add_u64 v[4:5], v[60:61], 1, s[56:57]
	global_store_short v[4:5], v6, off
	v_cvt_pk_bf16_f32 v6, v9, s0
	v_lshl_add_u64 v[4:5], v[64:65], 1, s[56:57]
	global_store_short v[4:5], v6, off
	v_cvt_pk_bf16_f32 v6, v10, s0
	v_lshl_add_u64 v[4:5], v[78:79], 1, s[56:57]
	global_store_short v[4:5], v6, off
	v_cvt_pk_bf16_f32 v6, v11, s0
	v_lshl_add_u64 v[4:5], v[82:83], 1, s[56:57]
	global_store_short v[4:5], v6, off
	v_cvt_pk_bf16_f32 v6, v12, s0
	v_lshl_add_u64 v[4:5], v[56:57], 1, s[56:57]
	global_store_short v[4:5], v6, off
	v_cvt_pk_bf16_f32 v6, v13, s0
	v_lshl_add_u64 v[4:5], v[70:71], 1, s[56:57]
	global_store_short v[4:5], v6, off
	v_cvt_pk_bf16_f32 v6, v14, s0
	v_lshl_add_u64 v[4:5], v[76:77], 1, s[56:57]
	global_store_short v[4:5], v6, off
	v_cvt_pk_bf16_f32 v6, v15, s0
	v_lshl_add_u64 v[4:5], v[80:81], 1, s[56:57]
	global_store_short v[4:5], v6, off
	v_cvt_pk_bf16_f32 v0, v0, s0
	v_lshl_add_u64 v[4:5], v[54:55], 1, s[56:57]
	global_store_short v[4:5], v0, off
	v_cvt_pk_bf16_f32 v4, v1, s0
	v_lshl_add_u64 v[0:1], v[68:69], 1, s[56:57]
	global_store_short v[0:1], v4, off
	v_cvt_pk_bf16_f32 v2, v2, s0
	v_lshl_add_u64 v[0:1], v[74:75], 1, s[56:57]
	global_store_short v[0:1], v2, off
	v_cvt_pk_bf16_f32 v2, v3, s0
	v_lshl_add_u64 v[0:1], v[84:85], 1, s[56:57]
	global_store_short v[0:1], v2, off
	s_cbranch_scc0 .LBB0_853

.LBB0_1833:
	s_or_b64 exec, exec, s[0:1]
	global_load_dwordx4 v[0:3], v[38:39], off offset:256
	global_load_dwordx4 v[92:95], v[38:39], off offset:320
	global_load_dwordx4 v[96:99], v[38:39], off offset:384
	global_load_dwordx4 v[100:103], v[38:39], off offset:448
	ds_read_b128 v[4:7], v151 offset:32768
	ds_read_b128 v[8:11], v151 offset:36864
	ds_read_b128 v[12:15], v151 offset:40960
	ds_read_b128 v[16:19], v151 offset:45056
	ds_read_b128 v[104:107], v152 offset:32768
	ds_read_b128 v[108:111], v152 offset:36864
	ds_read_b128 v[112:115], v152 offset:40960
	ds_read_b128 v[116:119], v152 offset:45056
	ds_read_b128 v[156:159], v153 offset:32768
	ds_read_b128 v[160:163], v153 offset:36864
	ds_read_b128 v[164:167], v153 offset:40960
	ds_read_b128 v[168:171], v153 offset:45056
	s_add_i32 s12, s12, s66
	s_add_i32 s13, s13, s14
	s_add_i32 s16, s16, s17
	v_add_u32_e32 v134, s15, v134
	s_cmpk_lt_i32 s12, 0x1e0
	s_waitcnt vmcnt(3) lgkmcnt(8)
	v_mfma_f32_16x16x32_bf16 v[4:7], v[0:3], v[4:7], 0
	v_mfma_f32_16x16x32_bf16 v[8:11], v[0:3], v[8:11], 0
	v_mfma_f32_16x16x32_bf16 v[12:15], v[0:3], v[12:15], 0
	v_mfma_f32_16x16x32_bf16 v[0:3], v[0:3], v[16:19], 0
	ds_read_b128 v[172:175], v154 offset:32768
	ds_read_b128 v[176:179], v154 offset:36864
	ds_read_b128 v[180:183], v154 offset:40960
	ds_read_b128 v[184:187], v154 offset:45056
	s_waitcnt vmcnt(2) lgkmcnt(8)
	v_mfma_f32_16x16x32_bf16 v[4:7], v[92:95], v[104:107], v[4:7]
	v_mfma_f32_16x16x32_bf16 v[8:11], v[92:95], v[108:111], v[8:11]
	v_mfma_f32_16x16x32_bf16 v[12:15], v[92:95], v[112:115], v[12:15]
	v_mfma_f32_16x16x32_bf16 v[0:3], v[92:95], v[116:119], v[0:3]
	s_waitcnt vmcnt(1) lgkmcnt(4)
	v_mfma_f32_16x16x32_bf16 v[4:7], v[96:99], v[156:159], v[4:7]
	v_mfma_f32_16x16x32_bf16 v[8:11], v[96:99], v[160:163], v[8:11]
	v_mfma_f32_16x16x32_bf16 v[12:15], v[96:99], v[164:167], v[12:15]
	v_mfma_f32_16x16x32_bf16 v[0:3], v[96:99], v[168:171], v[0:3]
	s_waitcnt vmcnt(0) lgkmcnt(0)
	v_mfma_f32_16x16x32_bf16 v[4:7], v[100:103], v[172:175], v[4:7]
	v_mfma_f32_16x16x32_bf16 v[8:11], v[100:103], v[176:179], v[8:11]
	v_mfma_f32_16x16x32_bf16 v[12:15], v[100:103], v[180:183], v[12:15]
	v_mfma_f32_16x16x32_bf16 v[0:3], v[100:103], v[184:187], v[0:3]
	s_nop 7
	s_nop 1
	v_cvt_pk_bf16_f32 v4, v4, s0
	v_cvt_pk_bf16_f32 v6, v6, s0
	v_lshl_add_u64 v[16:17], v[58:59], 1, s[56:57]
	global_store_short v[16:17], v4, off
	v_cvt_pk_bf16_f32 v16, v5, s0
	v_lshl_add_u64 v[4:5], v[66:67], 1, s[56:57]
	global_store_short v[4:5], v16, off
	v_lshl_add_u64 v[4:5], v[72:73], 1, s[56:57]
	global_store_short v[4:5], v6, off
	v_cvt_pk_bf16_f32 v6, v7, s0
	v_lshl_add_u64 v[4:5], v[56:57], 1, s[56:57]
	global_store_short v[4:5], v6, off
	v_cvt_pk_bf16_f32 v6, v8, s0
	v_lshl_add_u64 v[4:5], v[42:43], 1, s[56:57]
	global_store_short v[4:5], v6, off
	v_cvt_pk_bf16_f32 v6, v9, s0
	v_lshl_add_u64 v[4:5], v[62:63], 1, s[56:57]
	global_store_short v[4:5], v6, off
	v_cvt_pk_bf16_f32 v6, v10, s0
	v_lshl_add_u64 v[4:5], v[78:79], 1, s[56:57]
	global_store_short v[4:5], v6, off
	v_cvt_pk_bf16_f32 v6, v11, s0
	v_lshl_add_u64 v[4:5], v[82:83], 1, s[56:57]
	global_store_short v[4:5], v6, off
	v_cvt_pk_bf16_f32 v6, v12, s0
	v_lshl_add_u64 v[4:5], v[40:41], 1, s[56:57]
	global_store_short v[4:5], v6, off
	v_cvt_pk_bf16_f32 v6, v13, s0
	v_lshl_add_u64 v[4:5], v[70:71], 1, s[56:57]
	global_store_short v[4:5], v6, off
	v_cvt_pk_bf16_f32 v6, v14, s0
	v_lshl_add_u64 v[4:5], v[76:77], 1, s[56:57]
	global_store_short v[4:5], v6, off
	v_cvt_pk_bf16_f32 v6, v15, s0
	v_lshl_add_u64 v[4:5], v[80:81], 1, s[56:57]
	global_store_short v[4:5], v6, off
	v_cvt_pk_bf16_f32 v0, v0, s0
	v_lshl_add_u64 v[4:5], v[36:37], 1, s[56:57]
	global_store_short v[4:5], v0, off
	v_cvt_pk_bf16_f32 v4, v1, s0
	v_lshl_add_u64 v[0:1], v[68:69], 1, s[56:57]
	global_store_short v[0:1], v4, off
	v_cvt_pk_bf16_f32 v2, v2, s0
	v_lshl_add_u64 v[0:1], v[74:75], 1, s[56:57]
	global_store_short v[0:1], v2, off
	v_cvt_pk_bf16_f32 v2, v3, s0
	v_lshl_add_u64 v[0:1], v[84:85], 1, s[56:57]
	global_store_short v[0:1], v2, off
	s_cbranch_scc0 .LBB0_1850
